# v55 + EpiRes epilogues: counted vmcnt per row-group instead of vmcnt(0) after the 16 residual-stream loads (epilogue de-serialisation)
# baseline (speedup 1.0000x reference)
.LBB0_514:
	v_mov_b32_e32 v70, v0
	s_lshl_b32 s0, s40, 8
	s_add_i32 s0, s0, s54
	v_bfe_u32 v239, v70, 4, 2
	v_and_or_b32 v228, v70, 15, s0
	s_or_b32 s0, s64, s67
	v_lshlrev_b32_e32 v70, 3, v239
	v_or_b32_e32 v214, s0, v70
	v_or_b32_e32 v70, s67, v70
	v_ashrrev_i32_e32 v215, 31, v214
	v_ashrrev_i32_e32 v229, 31, v228
	v_lshlrev_b32_e32 v238, 2, v70
	v_lshl_add_u64 v[70:71], v[214:215], 1, s[10:11]
	v_lshlrev_b64 v[72:73], 12, v[228:229]
	v_lshl_add_u64 v[72:73], v[70:71], 0, v[72:73]
	global_load_dwordx4 v[190:193], v[72:73], off
	global_load_dwordx4 v[186:189], v[72:73], off offset:256
	v_or_b32_e32 v230, 16, v228
	v_ashrrev_i32_e32 v231, 31, v230
	v_lshlrev_b64 v[72:73], 12, v[230:231]
	v_or_b32_e32 v226, 32, v228
	v_lshl_add_u64 v[72:73], v[70:71], 0, v[72:73]
	v_ashrrev_i32_e32 v227, 31, v226
	global_load_dwordx4 v[182:185], v[72:73], off
	global_load_dwordx4 v[178:181], v[72:73], off offset:256
	v_lshlrev_b64 v[72:73], 12, v[226:227]
	v_or_b32_e32 v224, 48, v228
	v_lshl_add_u64 v[72:73], v[70:71], 0, v[72:73]
	v_ashrrev_i32_e32 v225, 31, v224
	global_load_dwordx4 v[166:169], v[72:73], off
	global_load_dwordx4 v[162:165], v[72:73], off offset:256
	v_lshlrev_b64 v[72:73], 12, v[224:225]
	v_add_u32_e32 v222, 0x80, v228
	v_lshl_add_u64 v[72:73], v[70:71], 0, v[72:73]
	v_ashrrev_i32_e32 v223, 31, v222
	global_load_dwordx4 v[158:161], v[72:73], off
	global_load_dwordx4 v[154:157], v[72:73], off offset:256
	v_lshlrev_b64 v[72:73], 12, v[222:223]
	v_add_u32_e32 v220, 0x90, v228
	v_lshl_add_u64 v[72:73], v[70:71], 0, v[72:73]
	v_ashrrev_i32_e32 v221, 31, v220
	global_load_dwordx4 v[142:145], v[72:73], off
	global_load_dwordx4 v[134:137], v[72:73], off offset:256
	v_lshlrev_b64 v[72:73], 12, v[220:221]
	v_add_u32_e32 v218, 0xa0, v228
	v_lshl_add_u64 v[72:73], v[70:71], 0, v[72:73]
	v_ashrrev_i32_e32 v219, 31, v218
	global_load_dwordx4 v[126:129], v[72:73], off
	global_load_dwordx4 v[114:117], v[72:73], off offset:256
	v_lshlrev_b64 v[72:73], 12, v[218:219]
	v_add_u32_e32 v216, 0xb0, v228
	v_lshl_add_u64 v[72:73], v[70:71], 0, v[72:73]
	v_ashrrev_i32_e32 v217, 31, v216
	global_load_dwordx4 v[102:105], v[72:73], off
	global_load_dwordx4 v[90:93], v[72:73], off offset:256
	v_lshlrev_b64 v[72:73], 12, v[216:217]
	v_lshl_add_u64 v[70:71], v[70:71], 0, v[72:73]
	global_load_dwordx4 v[78:81], v[70:71], off
	s_nop 0
	global_load_dwordx4 v[70:73], v[70:71], off offset:256
	v_add_u32_e32 v238, 0, v238
	v_add_u32_e32 v238, 0x24400, v238
	v_lshlrev_b64 v[240:241], 11, v[228:229]
	v_lshl_add_u64 v[248:249], v[240:241], 0, v[214:215]
	ds_read_b128 v[240:243], v238
	ds_read_b128 v[244:247], v238 offset:16
	v_cmp_eq_u32_e32 vcc, 0, v239
	s_waitcnt vmcnt(14)
	v_lshlrev_b32_e32 v250, 16, v190
	v_and_b32_e32 v251, 0xffff0000, v190
	v_lshlrev_b32_e32 v190, 16, v191
	v_and_b32_e32 v191, 0xffff0000, v191
	s_waitcnt lgkmcnt(1)
	v_pk_fma_f32 v[176:177], v[176:177], v[242:243], v[190:191]
	v_lshlrev_b32_e32 v190, 16, v192
	v_and_b32_e32 v191, 0xffff0000, v192
	v_lshlrev_b32_e32 v192, 16, v193
	v_and_b32_e32 v193, 0xffff0000, v193
	s_waitcnt lgkmcnt(0)
	v_pk_fma_f32 v[192:193], v[172:173], v[246:247], v[192:193]
	v_pk_fma_f32 v[172:173], v[170:171], v[244:245], v[190:191]
	v_lshlrev_b64 v[190:191], 1, v[248:249]
	v_pk_fma_f32 v[174:175], v[174:175], v[240:241], v[250:251]
	s_nop 0
	v_cvt_pk_bf16_f32 v170, v174, v175
	v_cvt_pk_bf16_f32 v171, v176, v177
	v_cvt_pk_bf16_f32 v172, v172, v173
	v_cvt_pk_bf16_f32 v173, v192, v193
	v_lshl_add_u64 v[192:193], s[12:13], 0, v[190:191]
	v_and_b32_e32 v241, 0xffff0000, v170
	v_and_b32_e32 v243, 0xffff0000, v171
	global_store_dwordx4 v[192:193], v[170:173], off
	v_lshlrev_b32_e32 v240, 16, v170
	v_lshlrev_b32_e32 v242, 16, v171
	v_mul_f32_e32 v170, v241, v241
	v_mul_f32_e32 v171, v243, v243
	v_and_b32_e32 v245, 0xffff0000, v172
	v_and_b32_e32 v247, 0xffff0000, v173
	v_fmac_f32_e32 v170, v240, v240
	v_fmac_f32_e32 v171, v242, v242
	v_lshlrev_b32_e32 v244, 16, v172
	v_lshlrev_b32_e32 v246, 16, v173
	v_add_f32_e32 v170, v170, v171
	v_mul_f32_e32 v171, v245, v245
	v_mul_f32_e32 v172, v247, v247
	v_fmac_f32_e32 v171, v244, v244
	v_fmac_f32_e32 v172, v246, v246
	v_add_f32_e32 v171, v171, v172
	v_add_f32_e32 v239, v170, v171
	ds_read_b128 v[170:173], v238 offset:1024
	ds_read_b128 v[174:177], v238 offset:1040
	v_lshl_add_u64 v[190:191], s[36:37], 0, v[190:191]
	s_waitcnt lgkmcnt(1)
	v_pk_mul_f32 v[172:173], v[172:173], v[242:243]
	v_pk_mul_f32 v[170:171], v[170:171], v[240:241]
	s_waitcnt lgkmcnt(0)
	v_pk_mul_f32 v[176:177], v[176:177], v[246:247]
	v_pk_mul_f32 v[174:175], v[174:175], v[244:245]
	v_cvt_pk_bf16_f32 v170, v170, v171
	v_cvt_pk_bf16_f32 v171, v172, v173
	v_lshlrev_b32_e32 v240, 16, v186
	v_cvt_pk_bf16_f32 v172, v174, v175
	v_cvt_pk_bf16_f32 v173, v176, v177
	global_store_dwordx4 v[190:191], v[170:173], off
	ds_read_b128 v[170:173], v238 offset:512
	ds_read_b128 v[174:177], v238 offset:528
	v_and_b32_e32 v241, 0xffff0000, v186
	v_lshlrev_b32_e32 v186, 16, v187
	v_and_b32_e32 v187, 0xffff0000, v187
	s_waitcnt lgkmcnt(1)
	v_pk_fma_f32 v[152:153], v[152:153], v[172:173], v[186:187]
	v_pk_fma_f32 v[150:151], v[150:151], v[170:171], v[240:241]
	v_lshlrev_b32_e32 v170, 16, v188
	v_and_b32_e32 v171, 0xffff0000, v188
	v_lshlrev_b32_e32 v172, 16, v189
	v_and_b32_e32 v173, 0xffff0000, v189
	s_waitcnt lgkmcnt(0)
	v_pk_fma_f32 v[172:173], v[148:149], v[176:177], v[172:173]
	v_pk_fma_f32 v[148:149], v[146:147], v[174:175], v[170:171]
	v_cvt_pk_bf16_f32 v146, v150, v151
	v_cvt_pk_bf16_f32 v147, v152, v153
	s_nop 0
	v_cvt_pk_bf16_f32 v148, v148, v149
	v_cvt_pk_bf16_f32 v149, v172, v173
	v_and_b32_e32 v171, 0xffff0000, v146
	v_and_b32_e32 v173, 0xffff0000, v147
	global_store_dwordx4 v[192:193], v[146:149], off offset:256
	v_lshlrev_b32_e32 v170, 16, v146
	v_lshlrev_b32_e32 v172, 16, v147
	v_mul_f32_e32 v146, v171, v171
	v_mul_f32_e32 v147, v173, v173
	v_and_b32_e32 v175, 0xffff0000, v148
	v_and_b32_e32 v177, 0xffff0000, v149
	v_fmac_f32_e32 v146, v170, v170
	v_fmac_f32_e32 v147, v172, v172
	v_lshlrev_b32_e32 v174, 16, v148
	v_lshlrev_b32_e32 v176, 16, v149
	v_add_f32_e32 v146, v146, v147
	v_mul_f32_e32 v147, v175, v175
	v_mul_f32_e32 v148, v177, v177
	v_fmac_f32_e32 v147, v174, v174
	v_fmac_f32_e32 v148, v176, v176
	v_add_f32_e32 v147, v147, v148
	v_add_f32_e32 v146, v146, v147
	v_add_f32_e32 v186, v239, v146
	ds_read_b128 v[146:149], v238 offset:1536
	ds_read_b128 v[150:153], v238 offset:1552
	s_waitcnt lgkmcnt(1)
	v_pk_mul_f32 v[146:147], v[146:147], v[170:171]
	v_pk_mul_f32 v[148:149], v[148:149], v[172:173]
	v_cvt_pk_bf16_f32 v146, v146, v147
	s_waitcnt lgkmcnt(0)
	v_pk_mul_f32 v[152:153], v[152:153], v[176:177]
	v_pk_mul_f32 v[150:151], v[150:151], v[174:175]
	v_cvt_pk_bf16_f32 v147, v148, v149
	s_nop 0
	v_cvt_pk_bf16_f32 v148, v150, v151
	v_cvt_pk_bf16_f32 v149, v152, v153
	global_store_dwordx4 v[190:191], v[146:149], off offset:256
	ds_swizzle_b32 v146, v186 offset:swizzle(SWAP,16)
	s_waitcnt lgkmcnt(0)
	v_add_f32_e32 v148, v186, v146
	v_mov_b32_e32 v149, v148
	s_nop 1
	v_permlane32_swap_b32_e32 v148, v149
	v_lshl_add_u64 v[146:147], v[228:229], 2, s[38:39]
	s_and_saveexec_b64 s[22:23], vcc
	s_cbranch_execz .LBB0_516
	v_add_f32_e32 v148, v148, v149
	v_fma_f32 v148, v148, s74, 0.5
	v_cvt_u32_f32_e32 v148, v148
	global_atomic_add v[146:147], v148, off
.LBB0_516:
	s_or_b64 exec, exec, s[22:23]
	v_lshlrev_b64 v[148:149], 11, v[230:231]
	v_lshl_add_u64 v[152:153], v[148:149], 0, v[214:215]
	ds_read_b128 v[148:151], v238
	ds_read_b128 v[170:173], v238 offset:16
	s_waitcnt vmcnt(17)
	v_lshlrev_b32_e32 v174, 16, v182
	v_and_b32_e32 v175, 0xffff0000, v182
	v_lshlrev_b32_e32 v176, 16, v183
	v_and_b32_e32 v177, 0xffff0000, v183
	s_waitcnt lgkmcnt(1)
	v_pk_fma_f32 v[140:141], v[140:141], v[150:151], v[176:177]
	v_pk_fma_f32 v[138:139], v[138:139], v[148:149], v[174:175]
	v_lshlrev_b32_e32 v148, 16, v184
	v_and_b32_e32 v149, 0xffff0000, v184
	v_lshlrev_b32_e32 v150, 16, v185
	v_and_b32_e32 v151, 0xffff0000, v185
	s_waitcnt lgkmcnt(0)
	v_pk_fma_f32 v[150:151], v[132:133], v[172:173], v[150:151]
	v_pk_fma_f32 v[132:133], v[130:131], v[170:171], v[148:149]
	v_lshlrev_b64 v[148:149], 1, v[152:153]
	v_cvt_pk_bf16_f32 v130, v138, v139
	v_cvt_pk_bf16_f32 v131, v140, v141
	v_cvt_pk_bf16_f32 v132, v132, v133
	v_cvt_pk_bf16_f32 v133, v150, v151
	v_lshl_add_u64 v[150:151], s[12:13], 0, v[148:149]
	v_and_b32_e32 v153, 0xffff0000, v130
	v_and_b32_e32 v171, 0xffff0000, v131
	global_store_dwordx4 v[150:151], v[130:133], off
	v_lshlrev_b32_e32 v152, 16, v130
	v_lshlrev_b32_e32 v170, 16, v131
	v_and_b32_e32 v173, 0xffff0000, v132
	v_and_b32_e32 v175, 0xffff0000, v133
	v_mul_f32_e32 v130, v153, v153
	v_mul_f32_e32 v131, v171, v171
	v_lshlrev_b32_e32 v172, 16, v132
	v_lshlrev_b32_e32 v174, 16, v133
	v_fmac_f32_e32 v130, v152, v152
	v_fmac_f32_e32 v131, v170, v170
	v_mul_f32_e32 v138, v173, v173
	v_mul_f32_e32 v139, v175, v175
	v_add_f32_e32 v176, v130, v131
	v_fmac_f32_e32 v138, v172, v172
	v_fmac_f32_e32 v139, v174, v174
	ds_read_b128 v[130:133], v238 offset:1024
	v_add_f32_e32 v177, v138, v139
	ds_read_b128 v[138:141], v238 offset:1040
	v_lshl_add_u64 v[148:149], s[36:37], 0, v[148:149]
	v_add_f32_e32 v176, v176, v177
	s_waitcnt lgkmcnt(1)
	v_pk_mul_f32 v[132:133], v[132:133], v[170:171]
	v_pk_mul_f32 v[130:131], v[130:131], v[152:153]
	s_waitcnt lgkmcnt(0)
	v_pk_mul_f32 v[140:141], v[140:141], v[174:175]
	v_pk_mul_f32 v[138:139], v[138:139], v[172:173]
	v_cvt_pk_bf16_f32 v130, v130, v131
	v_cvt_pk_bf16_f32 v131, v132, v133
	v_lshlrev_b32_e32 v152, 16, v178
	v_cvt_pk_bf16_f32 v132, v138, v139
	v_cvt_pk_bf16_f32 v133, v140, v141
	global_store_dwordx4 v[148:149], v[130:133], off
	ds_read_b128 v[130:133], v238 offset:512
	ds_read_b128 v[138:141], v238 offset:528
	v_and_b32_e32 v153, 0xffff0000, v178
	v_lshlrev_b32_e32 v170, 16, v179
	v_and_b32_e32 v171, 0xffff0000, v179
	s_waitcnt lgkmcnt(1)
	v_pk_fma_f32 v[124:125], v[124:125], v[132:133], v[170:171]
	v_pk_fma_f32 v[122:123], v[122:123], v[130:131], v[152:153]
	v_lshlrev_b32_e32 v130, 16, v180
	v_and_b32_e32 v131, 0xffff0000, v180
	v_lshlrev_b32_e32 v132, 16, v181
	v_and_b32_e32 v133, 0xffff0000, v181
	s_waitcnt lgkmcnt(0)
	v_pk_fma_f32 v[132:133], v[120:121], v[140:141], v[132:133]
	v_pk_fma_f32 v[120:121], v[118:119], v[138:139], v[130:131]
	v_cvt_pk_bf16_f32 v118, v122, v123
	v_cvt_pk_bf16_f32 v119, v124, v125
	s_nop 0
	v_cvt_pk_bf16_f32 v120, v120, v121
	v_cvt_pk_bf16_f32 v121, v132, v133
	v_and_b32_e32 v131, 0xffff0000, v118
	v_and_b32_e32 v133, 0xffff0000, v119
	global_store_dwordx4 v[150:151], v[118:121], off offset:256
	v_lshlrev_b32_e32 v130, 16, v118
	v_lshlrev_b32_e32 v132, 16, v119
	v_mul_f32_e32 v118, v131, v131
	v_mul_f32_e32 v119, v133, v133
	v_and_b32_e32 v139, 0xffff0000, v120
	v_and_b32_e32 v141, 0xffff0000, v121
	v_fmac_f32_e32 v118, v130, v130
	v_fmac_f32_e32 v119, v132, v132
	v_lshlrev_b32_e32 v138, 16, v120
	v_lshlrev_b32_e32 v140, 16, v121
	v_add_f32_e32 v150, v118, v119
	v_mul_f32_e32 v122, v139, v139
	v_mul_f32_e32 v123, v141, v141
	ds_read_b128 v[118:121], v238 offset:1536
	v_fmac_f32_e32 v122, v138, v138
	v_fmac_f32_e32 v123, v140, v140
	v_add_f32_e32 v151, v122, v123
	v_add_f32_e32 v150, v150, v151
	v_add_f32_e32 v150, v176, v150
	ds_read_b128 v[122:125], v238 offset:1552
	s_waitcnt lgkmcnt(1)
	v_pk_mul_f32 v[118:119], v[118:119], v[130:131]
	ds_swizzle_b32 v130, v150 offset:swizzle(SWAP,16)
	v_pk_mul_f32 v[120:121], v[120:121], v[132:133]
	v_cvt_pk_bf16_f32 v118, v118, v119
	s_waitcnt lgkmcnt(1)
	v_pk_mul_f32 v[124:125], v[124:125], v[140:141]
	v_pk_mul_f32 v[122:123], v[122:123], v[138:139]
	v_cvt_pk_bf16_f32 v119, v120, v121
	s_nop 0
	v_cvt_pk_bf16_f32 v120, v122, v123
	v_cvt_pk_bf16_f32 v121, v124, v125
	global_store_dwordx4 v[148:149], v[118:121], off offset:256
	s_waitcnt lgkmcnt(0)
	s_nop 0
	v_add_f32_e32 v118, v150, v130
	v_mov_b32_e32 v119, v118
	s_nop 1
	v_permlane32_swap_b32_e32 v118, v119
	s_and_saveexec_b64 s[22:23], vcc
	s_cbranch_execz .LBB0_518
	v_add_f32_e32 v118, v118, v119
	v_fma_f32 v118, v118, s74, 0.5
	v_cvt_u32_f32_e32 v118, v118
	global_atomic_add v[146:147], v118, off offset:64
.LBB0_518:
	s_or_b64 exec, exec, s[22:23]
	v_lshlrev_b64 v[118:119], 11, v[226:227]
	v_lshl_add_u64 v[130:131], v[118:119], 0, v[214:215]
	ds_read_b128 v[118:121], v238
	ds_read_b128 v[122:125], v238 offset:16
	s_waitcnt vmcnt(20)
	v_lshlrev_b32_e32 v132, 16, v166
	v_and_b32_e32 v133, 0xffff0000, v166
	v_lshlrev_b32_e32 v138, 16, v167
	v_and_b32_e32 v139, 0xffff0000, v167
	s_waitcnt lgkmcnt(1)
	v_pk_fma_f32 v[112:113], v[112:113], v[120:121], v[138:139]
	v_pk_fma_f32 v[110:111], v[110:111], v[118:119], v[132:133]
	v_lshlrev_b32_e32 v118, 16, v168
	v_and_b32_e32 v119, 0xffff0000, v168
	v_lshlrev_b32_e32 v120, 16, v169
	v_and_b32_e32 v121, 0xffff0000, v169
	s_waitcnt lgkmcnt(0)
	v_pk_fma_f32 v[120:121], v[108:109], v[124:125], v[120:121]
	v_pk_fma_f32 v[108:109], v[106:107], v[122:123], v[118:119]
	v_lshlrev_b64 v[118:119], 1, v[130:131]
	v_cvt_pk_bf16_f32 v106, v110, v111
	v_cvt_pk_bf16_f32 v107, v112, v113
	v_cvt_pk_bf16_f32 v108, v108, v109
	v_cvt_pk_bf16_f32 v109, v120, v121
	v_lshl_add_u64 v[120:121], s[12:13], 0, v[118:119]
	v_and_b32_e32 v123, 0xffff0000, v106
	v_and_b32_e32 v125, 0xffff0000, v107
	global_store_dwordx4 v[120:121], v[106:109], off
	v_lshlrev_b32_e32 v122, 16, v106
	v_lshlrev_b32_e32 v124, 16, v107
	v_and_b32_e32 v131, 0xffff0000, v108
	v_and_b32_e32 v133, 0xffff0000, v109
	v_mul_f32_e32 v106, v123, v123
	v_mul_f32_e32 v107, v125, v125
	v_lshlrev_b32_e32 v130, 16, v108
	v_lshlrev_b32_e32 v132, 16, v109
	v_fmac_f32_e32 v106, v122, v122
	v_fmac_f32_e32 v107, v124, v124
	v_mul_f32_e32 v110, v131, v131
	v_mul_f32_e32 v111, v133, v133
	v_add_f32_e32 v138, v106, v107
	v_fmac_f32_e32 v110, v130, v130
	v_fmac_f32_e32 v111, v132, v132
	ds_read_b128 v[106:109], v238 offset:1024
	v_add_f32_e32 v139, v110, v111
	ds_read_b128 v[110:113], v238 offset:1040
	v_lshl_add_u64 v[118:119], s[36:37], 0, v[118:119]
	v_add_f32_e32 v138, v138, v139
	s_waitcnt lgkmcnt(1)
	v_pk_mul_f32 v[108:109], v[108:109], v[124:125]
	v_pk_mul_f32 v[106:107], v[106:107], v[122:123]
	s_waitcnt lgkmcnt(0)
	v_pk_mul_f32 v[112:113], v[112:113], v[132:133]
	v_pk_mul_f32 v[110:111], v[110:111], v[130:131]
	v_cvt_pk_bf16_f32 v106, v106, v107
	v_cvt_pk_bf16_f32 v107, v108, v109
	v_lshlrev_b32_e32 v122, 16, v162
	v_cvt_pk_bf16_f32 v108, v110, v111
	v_cvt_pk_bf16_f32 v109, v112, v113
	global_store_dwordx4 v[118:119], v[106:109], off
	ds_read_b128 v[106:109], v238 offset:512
	ds_read_b128 v[110:113], v238 offset:528
	v_and_b32_e32 v123, 0xffff0000, v162
	v_lshlrev_b32_e32 v124, 16, v163
	v_and_b32_e32 v125, 0xffff0000, v163
	s_waitcnt lgkmcnt(1)
	v_pk_fma_f32 v[100:101], v[100:101], v[108:109], v[124:125]
	v_pk_fma_f32 v[98:99], v[98:99], v[106:107], v[122:123]
	v_lshlrev_b32_e32 v106, 16, v164
	v_and_b32_e32 v107, 0xffff0000, v164
	v_lshlrev_b32_e32 v108, 16, v165
	v_and_b32_e32 v109, 0xffff0000, v165
	s_waitcnt lgkmcnt(0)
	v_pk_fma_f32 v[108:109], v[96:97], v[112:113], v[108:109]
	v_pk_fma_f32 v[96:97], v[94:95], v[110:111], v[106:107]
	v_cvt_pk_bf16_f32 v94, v98, v99
	v_cvt_pk_bf16_f32 v95, v100, v101
	s_nop 0
	v_cvt_pk_bf16_f32 v96, v96, v97
	v_cvt_pk_bf16_f32 v97, v108, v109
	v_and_b32_e32 v107, 0xffff0000, v94
	v_and_b32_e32 v109, 0xffff0000, v95
	global_store_dwordx4 v[120:121], v[94:97], off offset:256
	v_lshlrev_b32_e32 v106, 16, v94
	v_lshlrev_b32_e32 v108, 16, v95
	v_mul_f32_e32 v94, v107, v107
	v_mul_f32_e32 v95, v109, v109
	v_and_b32_e32 v111, 0xffff0000, v96
	v_and_b32_e32 v113, 0xffff0000, v97
	v_fmac_f32_e32 v94, v106, v106
	v_fmac_f32_e32 v95, v108, v108
	v_lshlrev_b32_e32 v110, 16, v96
	v_lshlrev_b32_e32 v112, 16, v97
	v_add_f32_e32 v120, v94, v95
	v_mul_f32_e32 v98, v111, v111
	v_mul_f32_e32 v99, v113, v113
	ds_read_b128 v[94:97], v238 offset:1536
	v_fmac_f32_e32 v98, v110, v110
	v_fmac_f32_e32 v99, v112, v112
	v_add_f32_e32 v121, v98, v99
	v_add_f32_e32 v120, v120, v121
	v_add_f32_e32 v120, v138, v120
	ds_read_b128 v[98:101], v238 offset:1552
	s_waitcnt lgkmcnt(1)
	v_pk_mul_f32 v[94:95], v[94:95], v[106:107]
	ds_swizzle_b32 v106, v120 offset:swizzle(SWAP,16)
	v_pk_mul_f32 v[96:97], v[96:97], v[108:109]
	v_cvt_pk_bf16_f32 v94, v94, v95
	s_waitcnt lgkmcnt(1)
	v_pk_mul_f32 v[100:101], v[100:101], v[112:113]
	v_pk_mul_f32 v[98:99], v[98:99], v[110:111]
	v_cvt_pk_bf16_f32 v95, v96, v97
	s_nop 0
	v_cvt_pk_bf16_f32 v96, v98, v99
	v_cvt_pk_bf16_f32 v97, v100, v101
	global_store_dwordx4 v[118:119], v[94:97], off offset:256
	s_waitcnt lgkmcnt(0)
	s_nop 0
	v_add_f32_e32 v94, v120, v106
	v_mov_b32_e32 v95, v94
	s_nop 1
	v_permlane32_swap_b32_e32 v94, v95
	s_and_saveexec_b64 s[22:23], vcc
	s_cbranch_execz .LBB0_520
	v_add_f32_e32 v94, v94, v95
	v_fma_f32 v94, v94, s74, 0.5
	v_cvt_u32_f32_e32 v94, v94
	global_atomic_add v[146:147], v94, off offset:128
.LBB0_520:
	s_or_b64 exec, exec, s[22:23]
	v_lshlrev_b64 v[94:95], 11, v[224:225]
	v_lshl_add_u64 v[106:107], v[94:95], 0, v[214:215]
	ds_read_b128 v[94:97], v238
	ds_read_b128 v[98:101], v238 offset:16
	s_waitcnt vmcnt(23)
	v_lshlrev_b32_e32 v108, 16, v158
	v_and_b32_e32 v109, 0xffff0000, v158
	v_lshlrev_b32_e32 v110, 16, v159
	v_and_b32_e32 v111, 0xffff0000, v159
	s_waitcnt lgkmcnt(1)
	v_pk_fma_f32 v[88:89], v[88:89], v[96:97], v[110:111]
	v_pk_fma_f32 v[86:87], v[86:87], v[94:95], v[108:109]
	v_lshlrev_b32_e32 v94, 16, v160
	v_and_b32_e32 v95, 0xffff0000, v160
	v_lshlrev_b32_e32 v96, 16, v161
	v_and_b32_e32 v97, 0xffff0000, v161
	s_waitcnt lgkmcnt(0)
	v_pk_fma_f32 v[96:97], v[84:85], v[100:101], v[96:97]
	v_pk_fma_f32 v[84:85], v[82:83], v[98:99], v[94:95]
	v_lshlrev_b64 v[94:95], 1, v[106:107]
	v_cvt_pk_bf16_f32 v82, v86, v87
	v_cvt_pk_bf16_f32 v83, v88, v89
	v_cvt_pk_bf16_f32 v84, v84, v85
	v_cvt_pk_bf16_f32 v85, v96, v97
	v_lshl_add_u64 v[96:97], s[12:13], 0, v[94:95]
	v_and_b32_e32 v99, 0xffff0000, v82
	v_and_b32_e32 v101, 0xffff0000, v83
	global_store_dwordx4 v[96:97], v[82:85], off
	v_lshlrev_b32_e32 v98, 16, v82
	v_lshlrev_b32_e32 v100, 16, v83
	v_and_b32_e32 v107, 0xffff0000, v84
	v_and_b32_e32 v109, 0xffff0000, v85
	v_mul_f32_e32 v82, v99, v99
	v_mul_f32_e32 v83, v101, v101
	v_lshlrev_b32_e32 v106, 16, v84
	v_lshlrev_b32_e32 v108, 16, v85
	v_fmac_f32_e32 v82, v98, v98
	v_fmac_f32_e32 v83, v100, v100
	v_mul_f32_e32 v86, v107, v107
	v_mul_f32_e32 v87, v109, v109
	v_add_f32_e32 v110, v82, v83
	v_fmac_f32_e32 v86, v106, v106
	v_fmac_f32_e32 v87, v108, v108
	ds_read_b128 v[82:85], v238 offset:1024
	v_add_f32_e32 v111, v86, v87
	ds_read_b128 v[86:89], v238 offset:1040
	v_lshl_add_u64 v[94:95], s[36:37], 0, v[94:95]
	v_add_f32_e32 v110, v110, v111
	s_waitcnt lgkmcnt(1)
	v_pk_mul_f32 v[84:85], v[84:85], v[100:101]
	v_pk_mul_f32 v[82:83], v[82:83], v[98:99]
	s_waitcnt lgkmcnt(0)
	v_pk_mul_f32 v[88:89], v[88:89], v[108:109]
	v_pk_mul_f32 v[86:87], v[86:87], v[106:107]
	v_cvt_pk_bf16_f32 v82, v82, v83
	v_cvt_pk_bf16_f32 v83, v84, v85
	v_lshlrev_b32_e32 v98, 16, v154
	v_cvt_pk_bf16_f32 v84, v86, v87
	v_cvt_pk_bf16_f32 v85, v88, v89
	global_store_dwordx4 v[94:95], v[82:85], off
	ds_read_b128 v[82:85], v238 offset:512
	ds_read_b128 v[86:89], v238 offset:528
	v_and_b32_e32 v99, 0xffff0000, v154
	v_lshlrev_b32_e32 v100, 16, v155
	v_and_b32_e32 v101, 0xffff0000, v155
	s_waitcnt lgkmcnt(1)
	v_pk_fma_f32 v[76:77], v[76:77], v[84:85], v[100:101]
	v_pk_fma_f32 v[74:75], v[74:75], v[82:83], v[98:99]
	v_lshlrev_b32_e32 v82, 16, v156
	v_and_b32_e32 v83, 0xffff0000, v156
	v_lshlrev_b32_e32 v84, 16, v157
	v_and_b32_e32 v85, 0xffff0000, v157
	s_waitcnt lgkmcnt(0)
	v_pk_fma_f32 v[84:85], v[68:69], v[88:89], v[84:85]
	v_pk_fma_f32 v[68:69], v[66:67], v[86:87], v[82:83]
	v_cvt_pk_bf16_f32 v66, v74, v75
	v_cvt_pk_bf16_f32 v67, v76, v77
	s_nop 0
	v_cvt_pk_bf16_f32 v68, v68, v69
	v_cvt_pk_bf16_f32 v69, v84, v85
	v_and_b32_e32 v83, 0xffff0000, v66
	v_and_b32_e32 v85, 0xffff0000, v67
	global_store_dwordx4 v[96:97], v[66:69], off offset:256
	v_lshlrev_b32_e32 v82, 16, v66
	v_lshlrev_b32_e32 v84, 16, v67
	v_mul_f32_e32 v66, v83, v83
	v_mul_f32_e32 v67, v85, v85
	v_and_b32_e32 v87, 0xffff0000, v68
	v_and_b32_e32 v89, 0xffff0000, v69
	v_fmac_f32_e32 v66, v82, v82
	v_fmac_f32_e32 v67, v84, v84
	v_lshlrev_b32_e32 v86, 16, v68
	v_lshlrev_b32_e32 v88, 16, v69
	v_add_f32_e32 v96, v66, v67
	v_mul_f32_e32 v74, v87, v87
	v_mul_f32_e32 v75, v89, v89
	ds_read_b128 v[66:69], v238 offset:1536
	v_fmac_f32_e32 v74, v86, v86
	v_fmac_f32_e32 v75, v88, v88
	v_add_f32_e32 v97, v74, v75
	v_add_f32_e32 v96, v96, v97
	v_add_f32_e32 v96, v110, v96
	ds_read_b128 v[74:77], v238 offset:1552
	s_waitcnt lgkmcnt(1)
	v_pk_mul_f32 v[66:67], v[66:67], v[82:83]
	ds_swizzle_b32 v82, v96 offset:swizzle(SWAP,16)
	v_pk_mul_f32 v[68:69], v[68:69], v[84:85]
	v_cvt_pk_bf16_f32 v66, v66, v67
	s_waitcnt lgkmcnt(1)
	v_pk_mul_f32 v[76:77], v[76:77], v[88:89]
	v_pk_mul_f32 v[74:75], v[74:75], v[86:87]
	v_cvt_pk_bf16_f32 v67, v68, v69
	s_nop 0
	v_cvt_pk_bf16_f32 v68, v74, v75
	v_cvt_pk_bf16_f32 v69, v76, v77
	global_store_dwordx4 v[94:95], v[66:69], off offset:256
	s_waitcnt lgkmcnt(0)
	s_nop 0
	v_add_f32_e32 v66, v96, v82
	v_mov_b32_e32 v67, v66
	s_nop 1
	v_permlane32_swap_b32_e32 v66, v67
	s_and_saveexec_b64 s[22:23], vcc
	s_cbranch_execz .LBB0_522
	v_add_f32_e32 v66, v66, v67
	v_fma_f32 v66, v66, s74, 0.5
	v_cvt_u32_f32_e32 v66, v66
	global_atomic_add v[146:147], v66, off offset:192
.LBB0_522:
	s_or_b64 exec, exec, s[22:23]
	v_lshlrev_b64 v[66:67], 11, v[222:223]
	v_lshl_add_u64 v[82:83], v[66:67], 0, v[214:215]
	ds_read_b128 v[66:69], v238
	ds_read_b128 v[74:77], v238 offset:16
	s_waitcnt vmcnt(26)
	v_lshlrev_b32_e32 v84, 16, v142
	v_and_b32_e32 v85, 0xffff0000, v142
	v_lshlrev_b32_e32 v86, 16, v143
	v_and_b32_e32 v87, 0xffff0000, v143
	s_waitcnt lgkmcnt(1)
	v_pk_fma_f32 v[64:65], v[64:65], v[68:69], v[86:87]
	v_pk_fma_f32 v[62:63], v[62:63], v[66:67], v[84:85]
	v_lshlrev_b32_e32 v66, 16, v144
	v_and_b32_e32 v67, 0xffff0000, v144
	v_lshlrev_b32_e32 v68, 16, v145
	v_and_b32_e32 v69, 0xffff0000, v145
	s_waitcnt lgkmcnt(0)
	v_pk_fma_f32 v[68:69], v[60:61], v[76:77], v[68:69]
	v_pk_fma_f32 v[60:61], v[58:59], v[74:75], v[66:67]
	v_lshlrev_b64 v[66:67], 1, v[82:83]
	v_cvt_pk_bf16_f32 v58, v62, v63
	v_cvt_pk_bf16_f32 v59, v64, v65
	v_cvt_pk_bf16_f32 v60, v60, v61
	v_cvt_pk_bf16_f32 v61, v68, v69
	v_lshl_add_u64 v[68:69], s[12:13], 0, v[66:67]
	v_and_b32_e32 v75, 0xffff0000, v58
	v_and_b32_e32 v77, 0xffff0000, v59
	global_store_dwordx4 v[68:69], v[58:61], off
	v_lshlrev_b32_e32 v74, 16, v58
	v_lshlrev_b32_e32 v76, 16, v59
	v_and_b32_e32 v83, 0xffff0000, v60
	v_and_b32_e32 v85, 0xffff0000, v61
	v_mul_f32_e32 v58, v75, v75
	v_mul_f32_e32 v59, v77, v77
	v_lshlrev_b32_e32 v82, 16, v60
	v_lshlrev_b32_e32 v84, 16, v61
	v_fmac_f32_e32 v58, v74, v74
	v_fmac_f32_e32 v59, v76, v76
	v_mul_f32_e32 v62, v83, v83
	v_mul_f32_e32 v63, v85, v85
	v_add_f32_e32 v86, v58, v59
	v_fmac_f32_e32 v62, v82, v82
	v_fmac_f32_e32 v63, v84, v84
	ds_read_b128 v[58:61], v238 offset:1024
	v_add_f32_e32 v87, v62, v63
	ds_read_b128 v[62:65], v238 offset:1040
	v_lshl_add_u64 v[66:67], s[36:37], 0, v[66:67]
	v_add_f32_e32 v86, v86, v87
	s_waitcnt lgkmcnt(1)
	v_pk_mul_f32 v[60:61], v[60:61], v[76:77]
	v_pk_mul_f32 v[58:59], v[58:59], v[74:75]
	s_waitcnt lgkmcnt(0)
	v_pk_mul_f32 v[64:65], v[64:65], v[84:85]
	v_pk_mul_f32 v[62:63], v[62:63], v[82:83]
	v_cvt_pk_bf16_f32 v58, v58, v59
	v_cvt_pk_bf16_f32 v59, v60, v61
	v_lshlrev_b32_e32 v74, 16, v134
	v_cvt_pk_bf16_f32 v60, v62, v63
	v_cvt_pk_bf16_f32 v61, v64, v65
	global_store_dwordx4 v[66:67], v[58:61], off
	ds_read_b128 v[58:61], v238 offset:512
	ds_read_b128 v[62:65], v238 offset:528
	v_and_b32_e32 v75, 0xffff0000, v134
	v_lshlrev_b32_e32 v76, 16, v135
	v_and_b32_e32 v77, 0xffff0000, v135
	s_waitcnt lgkmcnt(1)
	v_pk_fma_f32 v[56:57], v[56:57], v[60:61], v[76:77]
	v_pk_fma_f32 v[54:55], v[54:55], v[58:59], v[74:75]
	v_lshlrev_b32_e32 v58, 16, v136
	v_and_b32_e32 v59, 0xffff0000, v136
	v_lshlrev_b32_e32 v60, 16, v137
	v_and_b32_e32 v61, 0xffff0000, v137
	s_waitcnt lgkmcnt(0)
	v_pk_fma_f32 v[60:61], v[52:53], v[64:65], v[60:61]
	v_pk_fma_f32 v[52:53], v[50:51], v[62:63], v[58:59]
	v_cvt_pk_bf16_f32 v50, v54, v55
	v_cvt_pk_bf16_f32 v51, v56, v57
	s_nop 0
	v_cvt_pk_bf16_f32 v52, v52, v53
	v_cvt_pk_bf16_f32 v53, v60, v61
	v_and_b32_e32 v59, 0xffff0000, v50
	v_and_b32_e32 v61, 0xffff0000, v51
	global_store_dwordx4 v[68:69], v[50:53], off offset:256
	v_lshlrev_b32_e32 v58, 16, v50
	v_lshlrev_b32_e32 v60, 16, v51
	v_mul_f32_e32 v50, v59, v59
	v_mul_f32_e32 v51, v61, v61
	v_and_b32_e32 v63, 0xffff0000, v52
	v_and_b32_e32 v65, 0xffff0000, v53
	v_fmac_f32_e32 v50, v58, v58
	v_fmac_f32_e32 v51, v60, v60
	v_lshlrev_b32_e32 v62, 16, v52
	v_lshlrev_b32_e32 v64, 16, v53
	v_add_f32_e32 v68, v50, v51
	v_mul_f32_e32 v54, v63, v63
	v_mul_f32_e32 v55, v65, v65
	ds_read_b128 v[50:53], v238 offset:1536
	v_fmac_f32_e32 v54, v62, v62
	v_fmac_f32_e32 v55, v64, v64
	v_add_f32_e32 v69, v54, v55
	v_add_f32_e32 v68, v68, v69
	v_add_f32_e32 v68, v86, v68
	ds_read_b128 v[54:57], v238 offset:1552
	s_waitcnt lgkmcnt(1)
	v_pk_mul_f32 v[50:51], v[50:51], v[58:59]
	ds_swizzle_b32 v58, v68 offset:swizzle(SWAP,16)
	v_pk_mul_f32 v[52:53], v[52:53], v[60:61]
	v_cvt_pk_bf16_f32 v50, v50, v51
	s_waitcnt lgkmcnt(1)
	v_pk_mul_f32 v[56:57], v[56:57], v[64:65]
	v_pk_mul_f32 v[54:55], v[54:55], v[62:63]
	v_cvt_pk_bf16_f32 v51, v52, v53
	s_nop 0
	v_cvt_pk_bf16_f32 v52, v54, v55
	v_cvt_pk_bf16_f32 v53, v56, v57
	global_store_dwordx4 v[66:67], v[50:53], off offset:256
	s_waitcnt lgkmcnt(0)
	s_nop 0
	v_add_f32_e32 v50, v68, v58
	v_mov_b32_e32 v51, v50
	s_nop 1
	v_permlane32_swap_b32_e32 v50, v51
	s_and_saveexec_b64 s[22:23], vcc
	s_cbranch_execz .LBB0_524
	v_add_f32_e32 v50, v50, v51
	v_fma_f32 v50, v50, s74, 0.5
	v_cvt_u32_f32_e32 v50, v50
	global_atomic_add v[146:147], v50, off offset:512
.LBB0_524:
	s_or_b64 exec, exec, s[22:23]
	v_lshlrev_b64 v[50:51], 11, v[220:221]
	v_lshl_add_u64 v[58:59], v[50:51], 0, v[214:215]
	ds_read_b128 v[50:53], v238
	ds_read_b128 v[54:57], v238 offset:16
	s_waitcnt vmcnt(29)
	v_lshlrev_b32_e32 v60, 16, v126
	v_and_b32_e32 v61, 0xffff0000, v126
	v_lshlrev_b32_e32 v62, 16, v127
	v_and_b32_e32 v63, 0xffff0000, v127
	s_waitcnt lgkmcnt(1)
	v_pk_fma_f32 v[48:49], v[48:49], v[52:53], v[62:63]
	v_pk_fma_f32 v[46:47], v[46:47], v[50:51], v[60:61]
	v_lshlrev_b32_e32 v50, 16, v128
	v_and_b32_e32 v51, 0xffff0000, v128
	v_lshlrev_b32_e32 v52, 16, v129
	v_and_b32_e32 v53, 0xffff0000, v129
	s_waitcnt lgkmcnt(0)
	v_pk_fma_f32 v[52:53], v[44:45], v[56:57], v[52:53]
	v_pk_fma_f32 v[44:45], v[42:43], v[54:55], v[50:51]
	v_lshlrev_b64 v[50:51], 1, v[58:59]
	v_cvt_pk_bf16_f32 v42, v46, v47
	v_cvt_pk_bf16_f32 v43, v48, v49
	v_cvt_pk_bf16_f32 v44, v44, v45
	v_cvt_pk_bf16_f32 v45, v52, v53
	v_lshl_add_u64 v[52:53], s[12:13], 0, v[50:51]
	v_and_b32_e32 v55, 0xffff0000, v42
	v_and_b32_e32 v57, 0xffff0000, v43
	global_store_dwordx4 v[52:53], v[42:45], off
	v_lshlrev_b32_e32 v54, 16, v42
	v_lshlrev_b32_e32 v56, 16, v43
	v_and_b32_e32 v59, 0xffff0000, v44
	v_and_b32_e32 v61, 0xffff0000, v45
	v_mul_f32_e32 v42, v55, v55
	v_mul_f32_e32 v43, v57, v57
	v_lshlrev_b32_e32 v58, 16, v44
	v_lshlrev_b32_e32 v60, 16, v45
	v_fmac_f32_e32 v42, v54, v54
	v_fmac_f32_e32 v43, v56, v56
	v_mul_f32_e32 v46, v59, v59
	v_mul_f32_e32 v47, v61, v61
	v_add_f32_e32 v62, v42, v43
	v_fmac_f32_e32 v46, v58, v58
	v_fmac_f32_e32 v47, v60, v60
	ds_read_b128 v[42:45], v238 offset:1024
	v_add_f32_e32 v63, v46, v47
	ds_read_b128 v[46:49], v238 offset:1040
	v_lshl_add_u64 v[50:51], s[36:37], 0, v[50:51]
	v_add_f32_e32 v62, v62, v63
	s_waitcnt lgkmcnt(1)
	v_pk_mul_f32 v[44:45], v[44:45], v[56:57]
	v_pk_mul_f32 v[42:43], v[42:43], v[54:55]
	s_waitcnt lgkmcnt(0)
	v_pk_mul_f32 v[48:49], v[48:49], v[60:61]
	v_pk_mul_f32 v[46:47], v[46:47], v[58:59]
	v_cvt_pk_bf16_f32 v42, v42, v43
	v_cvt_pk_bf16_f32 v43, v44, v45
	v_lshlrev_b32_e32 v54, 16, v114
	v_cvt_pk_bf16_f32 v44, v46, v47
	v_cvt_pk_bf16_f32 v45, v48, v49
	global_store_dwordx4 v[50:51], v[42:45], off
	ds_read_b128 v[42:45], v238 offset:512
	ds_read_b128 v[46:49], v238 offset:528
	v_and_b32_e32 v55, 0xffff0000, v114
	v_lshlrev_b32_e32 v56, 16, v115
	v_and_b32_e32 v57, 0xffff0000, v115
	s_waitcnt lgkmcnt(1)
	v_pk_fma_f32 v[40:41], v[40:41], v[44:45], v[56:57]
	v_pk_fma_f32 v[38:39], v[38:39], v[42:43], v[54:55]
	v_lshlrev_b32_e32 v42, 16, v116
	v_and_b32_e32 v43, 0xffff0000, v116
	v_lshlrev_b32_e32 v44, 16, v117
	v_and_b32_e32 v45, 0xffff0000, v117
	s_waitcnt lgkmcnt(0)
	v_pk_fma_f32 v[44:45], v[36:37], v[48:49], v[44:45]
	v_pk_fma_f32 v[36:37], v[34:35], v[46:47], v[42:43]
	v_cvt_pk_bf16_f32 v34, v38, v39
	v_cvt_pk_bf16_f32 v35, v40, v41
	s_nop 0
	v_cvt_pk_bf16_f32 v36, v36, v37
	v_cvt_pk_bf16_f32 v37, v44, v45
	v_and_b32_e32 v43, 0xffff0000, v34
	v_and_b32_e32 v45, 0xffff0000, v35
	global_store_dwordx4 v[52:53], v[34:37], off offset:256
	v_lshlrev_b32_e32 v42, 16, v34
	v_lshlrev_b32_e32 v44, 16, v35
	v_mul_f32_e32 v34, v43, v43
	v_mul_f32_e32 v35, v45, v45
	v_and_b32_e32 v47, 0xffff0000, v36
	v_and_b32_e32 v49, 0xffff0000, v37
	v_fmac_f32_e32 v34, v42, v42
	v_fmac_f32_e32 v35, v44, v44
	v_lshlrev_b32_e32 v46, 16, v36
	v_lshlrev_b32_e32 v48, 16, v37
	v_add_f32_e32 v52, v34, v35
	v_mul_f32_e32 v38, v47, v47
	v_mul_f32_e32 v39, v49, v49
	ds_read_b128 v[34:37], v238 offset:1536
	v_fmac_f32_e32 v38, v46, v46
	v_fmac_f32_e32 v39, v48, v48
	v_add_f32_e32 v53, v38, v39
	v_add_f32_e32 v52, v52, v53
	v_add_f32_e32 v52, v62, v52
	ds_read_b128 v[38:41], v238 offset:1552
	s_waitcnt lgkmcnt(1)
	v_pk_mul_f32 v[34:35], v[34:35], v[42:43]
	ds_swizzle_b32 v42, v52 offset:swizzle(SWAP,16)
	v_pk_mul_f32 v[36:37], v[36:37], v[44:45]
	v_cvt_pk_bf16_f32 v34, v34, v35
	s_waitcnt lgkmcnt(1)
	v_pk_mul_f32 v[40:41], v[40:41], v[48:49]
	v_pk_mul_f32 v[38:39], v[38:39], v[46:47]
	v_cvt_pk_bf16_f32 v35, v36, v37
	s_nop 0
	v_cvt_pk_bf16_f32 v36, v38, v39
	v_cvt_pk_bf16_f32 v37, v40, v41
	global_store_dwordx4 v[50:51], v[34:37], off offset:256
	s_waitcnt lgkmcnt(0)
	s_nop 0
	v_add_f32_e32 v34, v52, v42
	v_mov_b32_e32 v35, v34
	s_nop 1
	v_permlane32_swap_b32_e32 v34, v35
	s_and_saveexec_b64 s[22:23], vcc
	s_cbranch_execz .LBB0_526
	v_add_f32_e32 v34, v34, v35
	v_fma_f32 v34, v34, s74, 0.5
	v_cvt_u32_f32_e32 v34, v34
	global_atomic_add v[146:147], v34, off offset:576
.LBB0_526:
	s_or_b64 exec, exec, s[22:23]
	v_lshlrev_b64 v[34:35], 11, v[218:219]
	v_lshl_add_u64 v[42:43], v[34:35], 0, v[214:215]
	ds_read_b128 v[34:37], v238
	ds_read_b128 v[38:41], v238 offset:16
	s_waitcnt vmcnt(32)
	v_lshlrev_b32_e32 v44, 16, v102
	v_and_b32_e32 v45, 0xffff0000, v102
	v_lshlrev_b32_e32 v46, 16, v103
	v_and_b32_e32 v47, 0xffff0000, v103
	s_waitcnt lgkmcnt(1)
	v_pk_fma_f32 v[32:33], v[32:33], v[36:37], v[46:47]
	v_pk_fma_f32 v[30:31], v[30:31], v[34:35], v[44:45]
	v_lshlrev_b32_e32 v34, 16, v104
	v_and_b32_e32 v35, 0xffff0000, v104
	v_lshlrev_b32_e32 v36, 16, v105
	v_and_b32_e32 v37, 0xffff0000, v105
	s_waitcnt lgkmcnt(0)
	v_pk_fma_f32 v[36:37], v[28:29], v[40:41], v[36:37]
	v_pk_fma_f32 v[28:29], v[26:27], v[38:39], v[34:35]
	v_lshlrev_b64 v[34:35], 1, v[42:43]
	v_cvt_pk_bf16_f32 v26, v30, v31
	v_cvt_pk_bf16_f32 v27, v32, v33
	v_cvt_pk_bf16_f32 v28, v28, v29
	v_cvt_pk_bf16_f32 v29, v36, v37
	v_lshl_add_u64 v[36:37], s[12:13], 0, v[34:35]
	v_and_b32_e32 v39, 0xffff0000, v26
	v_and_b32_e32 v41, 0xffff0000, v27
	global_store_dwordx4 v[36:37], v[26:29], off
	v_lshlrev_b32_e32 v38, 16, v26
	v_lshlrev_b32_e32 v40, 16, v27
	v_and_b32_e32 v43, 0xffff0000, v28
	v_and_b32_e32 v45, 0xffff0000, v29
	v_mul_f32_e32 v26, v39, v39
	v_mul_f32_e32 v27, v41, v41
	v_lshlrev_b32_e32 v42, 16, v28
	v_lshlrev_b32_e32 v44, 16, v29
	v_fmac_f32_e32 v26, v38, v38
	v_fmac_f32_e32 v27, v40, v40
	v_mul_f32_e32 v30, v43, v43
	v_mul_f32_e32 v31, v45, v45
	v_add_f32_e32 v46, v26, v27
	v_fmac_f32_e32 v30, v42, v42
	v_fmac_f32_e32 v31, v44, v44
	ds_read_b128 v[26:29], v238 offset:1024
	v_add_f32_e32 v47, v30, v31
	ds_read_b128 v[30:33], v238 offset:1040
	v_lshl_add_u64 v[34:35], s[36:37], 0, v[34:35]
	v_add_f32_e32 v46, v46, v47
	s_waitcnt lgkmcnt(1)
	v_pk_mul_f32 v[28:29], v[28:29], v[40:41]
	v_pk_mul_f32 v[26:27], v[26:27], v[38:39]
	s_waitcnt lgkmcnt(0)
	v_pk_mul_f32 v[32:33], v[32:33], v[44:45]
	v_pk_mul_f32 v[30:31], v[30:31], v[42:43]
	v_cvt_pk_bf16_f32 v26, v26, v27
	v_cvt_pk_bf16_f32 v27, v28, v29
	v_lshlrev_b32_e32 v38, 16, v90
	v_cvt_pk_bf16_f32 v28, v30, v31
	v_cvt_pk_bf16_f32 v29, v32, v33
	global_store_dwordx4 v[34:35], v[26:29], off
	ds_read_b128 v[26:29], v238 offset:512
	ds_read_b128 v[30:33], v238 offset:528
	v_and_b32_e32 v39, 0xffff0000, v90
	v_lshlrev_b32_e32 v40, 16, v91
	v_and_b32_e32 v41, 0xffff0000, v91
	s_waitcnt lgkmcnt(1)
	v_pk_fma_f32 v[24:25], v[24:25], v[28:29], v[40:41]
	v_pk_fma_f32 v[22:23], v[22:23], v[26:27], v[38:39]
	v_lshlrev_b32_e32 v26, 16, v92
	v_and_b32_e32 v27, 0xffff0000, v92
	v_lshlrev_b32_e32 v28, 16, v93
	v_and_b32_e32 v29, 0xffff0000, v93
	s_waitcnt lgkmcnt(0)
	v_pk_fma_f32 v[28:29], v[20:21], v[32:33], v[28:29]
	v_pk_fma_f32 v[20:21], v[18:19], v[30:31], v[26:27]
	v_cvt_pk_bf16_f32 v18, v22, v23
	v_cvt_pk_bf16_f32 v19, v24, v25
	s_nop 0
	v_cvt_pk_bf16_f32 v20, v20, v21
	v_cvt_pk_bf16_f32 v21, v28, v29
	v_and_b32_e32 v27, 0xffff0000, v18
	v_and_b32_e32 v29, 0xffff0000, v19
	global_store_dwordx4 v[36:37], v[18:21], off offset:256
	v_lshlrev_b32_e32 v26, 16, v18
	v_lshlrev_b32_e32 v28, 16, v19
	v_mul_f32_e32 v18, v27, v27
	v_mul_f32_e32 v19, v29, v29
	v_and_b32_e32 v31, 0xffff0000, v20
	v_and_b32_e32 v33, 0xffff0000, v21
	v_fmac_f32_e32 v18, v26, v26
	v_fmac_f32_e32 v19, v28, v28
	v_lshlrev_b32_e32 v30, 16, v20
	v_lshlrev_b32_e32 v32, 16, v21
	v_add_f32_e32 v36, v18, v19
	v_mul_f32_e32 v22, v31, v31
	v_mul_f32_e32 v23, v33, v33
	ds_read_b128 v[18:21], v238 offset:1536
	v_fmac_f32_e32 v22, v30, v30
	v_fmac_f32_e32 v23, v32, v32
	v_add_f32_e32 v37, v22, v23
	v_add_f32_e32 v36, v36, v37
	v_add_f32_e32 v36, v46, v36
	ds_read_b128 v[22:25], v238 offset:1552
	s_waitcnt lgkmcnt(1)
	v_pk_mul_f32 v[18:19], v[18:19], v[26:27]
	ds_swizzle_b32 v26, v36 offset:swizzle(SWAP,16)
	v_pk_mul_f32 v[20:21], v[20:21], v[28:29]
	v_cvt_pk_bf16_f32 v18, v18, v19
	s_waitcnt lgkmcnt(1)
	v_pk_mul_f32 v[24:25], v[24:25], v[32:33]
	v_pk_mul_f32 v[22:23], v[22:23], v[30:31]
	v_cvt_pk_bf16_f32 v19, v20, v21
	s_nop 0
	v_cvt_pk_bf16_f32 v20, v22, v23
	v_cvt_pk_bf16_f32 v21, v24, v25
	global_store_dwordx4 v[34:35], v[18:21], off offset:256
	s_waitcnt lgkmcnt(0)
	s_nop 0
	v_add_f32_e32 v18, v36, v26
	v_mov_b32_e32 v19, v18
	s_nop 1
	v_permlane32_swap_b32_e32 v18, v19
	s_and_saveexec_b64 s[22:23], vcc
	s_cbranch_execz .LBB0_528
	v_add_f32_e32 v18, v18, v19
	v_fma_f32 v18, v18, s74, 0.5
	v_cvt_u32_f32_e32 v18, v18
	global_atomic_add v[146:147], v18, off offset:640
.LBB0_528:
	s_or_b64 exec, exec, s[22:23]
	v_lshlrev_b64 v[18:19], 11, v[216:217]
	v_lshl_add_u64 v[26:27], v[18:19], 0, v[214:215]
	ds_read_b128 v[18:21], v238
	ds_read_b128 v[22:25], v238 offset:16
	s_waitcnt vmcnt(35)
	v_lshlrev_b32_e32 v28, 16, v78
	v_and_b32_e32 v29, 0xffff0000, v78
	v_lshlrev_b32_e32 v30, 16, v79
	v_and_b32_e32 v31, 0xffff0000, v79
	s_waitcnt lgkmcnt(1)
	v_pk_fma_f32 v[16:17], v[16:17], v[20:21], v[30:31]
	v_pk_fma_f32 v[14:15], v[14:15], v[18:19], v[28:29]
	v_lshlrev_b32_e32 v18, 16, v80
	v_and_b32_e32 v19, 0xffff0000, v80
	v_lshlrev_b32_e32 v20, 16, v81
	v_and_b32_e32 v21, 0xffff0000, v81
	s_waitcnt lgkmcnt(0)
	v_pk_fma_f32 v[20:21], v[12:13], v[24:25], v[20:21]
	v_pk_fma_f32 v[12:13], v[10:11], v[22:23], v[18:19]
	v_lshlrev_b64 v[18:19], 1, v[26:27]
	v_cvt_pk_bf16_f32 v10, v14, v15
	v_cvt_pk_bf16_f32 v11, v16, v17
	v_cvt_pk_bf16_f32 v12, v12, v13
	v_cvt_pk_bf16_f32 v13, v20, v21
	v_lshl_add_u64 v[20:21], s[12:13], 0, v[18:19]
	v_and_b32_e32 v23, 0xffff0000, v10
	v_and_b32_e32 v25, 0xffff0000, v11
	global_store_dwordx4 v[20:21], v[10:13], off
	v_lshlrev_b32_e32 v22, 16, v10
	v_lshlrev_b32_e32 v24, 16, v11
	v_and_b32_e32 v27, 0xffff0000, v12
	v_and_b32_e32 v29, 0xffff0000, v13
	v_mul_f32_e32 v10, v23, v23
	v_mul_f32_e32 v11, v25, v25
	v_lshlrev_b32_e32 v26, 16, v12
	v_lshlrev_b32_e32 v28, 16, v13
	v_fmac_f32_e32 v10, v22, v22
	v_fmac_f32_e32 v11, v24, v24
	v_mul_f32_e32 v14, v27, v27
	v_mul_f32_e32 v15, v29, v29
	v_add_f32_e32 v30, v10, v11
	v_fmac_f32_e32 v14, v26, v26
	v_fmac_f32_e32 v15, v28, v28
	ds_read_b128 v[10:13], v238 offset:1024
	v_add_f32_e32 v31, v14, v15
	ds_read_b128 v[14:17], v238 offset:1040
	v_lshl_add_u64 v[18:19], s[36:37], 0, v[18:19]
	v_add_f32_e32 v30, v30, v31
	s_waitcnt lgkmcnt(1)
	v_pk_mul_f32 v[12:13], v[12:13], v[24:25]
	v_pk_mul_f32 v[10:11], v[10:11], v[22:23]
	s_waitcnt lgkmcnt(0)
	v_pk_mul_f32 v[16:17], v[16:17], v[28:29]
	v_pk_mul_f32 v[14:15], v[14:15], v[26:27]
	v_cvt_pk_bf16_f32 v10, v10, v11
	v_cvt_pk_bf16_f32 v11, v12, v13
	v_lshlrev_b32_e32 v22, 16, v70
	v_cvt_pk_bf16_f32 v12, v14, v15
	v_cvt_pk_bf16_f32 v13, v16, v17
	global_store_dwordx4 v[18:19], v[10:13], off
	ds_read_b128 v[10:13], v238 offset:512
	ds_read_b128 v[14:17], v238 offset:528
	v_and_b32_e32 v23, 0xffff0000, v70
	v_lshlrev_b32_e32 v24, 16, v71
	v_and_b32_e32 v25, 0xffff0000, v71
	s_waitcnt lgkmcnt(1)
	v_pk_fma_f32 v[8:9], v[8:9], v[12:13], v[24:25]
	v_pk_fma_f32 v[6:7], v[6:7], v[10:11], v[22:23]
	v_lshlrev_b32_e32 v10, 16, v72
	v_and_b32_e32 v11, 0xffff0000, v72
	v_lshlrev_b32_e32 v12, 16, v73
	v_and_b32_e32 v13, 0xffff0000, v73
	s_waitcnt lgkmcnt(0)
	v_pk_fma_f32 v[12:13], v[4:5], v[16:17], v[12:13]
	v_pk_fma_f32 v[4:5], v[2:3], v[14:15], v[10:11]
	v_cvt_pk_bf16_f32 v2, v6, v7
	v_cvt_pk_bf16_f32 v3, v8, v9
	s_nop 0
	v_cvt_pk_bf16_f32 v4, v4, v5
	v_cvt_pk_bf16_f32 v5, v12, v13
	v_and_b32_e32 v11, 0xffff0000, v2
	v_and_b32_e32 v13, 0xffff0000, v3
	global_store_dwordx4 v[20:21], v[2:5], off offset:256
	v_lshlrev_b32_e32 v10, 16, v2
	v_lshlrev_b32_e32 v12, 16, v3
	v_mul_f32_e32 v2, v11, v11
	v_mul_f32_e32 v3, v13, v13
	v_and_b32_e32 v15, 0xffff0000, v4
	v_and_b32_e32 v17, 0xffff0000, v5
	v_fmac_f32_e32 v2, v10, v10
	v_fmac_f32_e32 v3, v12, v12
	v_lshlrev_b32_e32 v14, 16, v4
	v_lshlrev_b32_e32 v16, 16, v5
	v_add_f32_e32 v20, v2, v3
	v_mul_f32_e32 v6, v15, v15
	v_mul_f32_e32 v7, v17, v17
	ds_read_b128 v[2:5], v238 offset:1536
	v_fmac_f32_e32 v6, v14, v14
	v_fmac_f32_e32 v7, v16, v16
	v_add_f32_e32 v21, v6, v7
	v_add_f32_e32 v20, v20, v21
	v_add_f32_e32 v20, v30, v20
	ds_read_b128 v[6:9], v238 offset:1552
	s_waitcnt lgkmcnt(1)
	v_pk_mul_f32 v[2:3], v[2:3], v[10:11]
	ds_swizzle_b32 v10, v20 offset:swizzle(SWAP,16)
	v_pk_mul_f32 v[4:5], v[4:5], v[12:13]
	v_cvt_pk_bf16_f32 v2, v2, v3
	s_waitcnt lgkmcnt(1)
	v_pk_mul_f32 v[8:9], v[8:9], v[16:17]
	v_pk_mul_f32 v[6:7], v[6:7], v[14:15]
	v_cvt_pk_bf16_f32 v3, v4, v5
	s_nop 0
	v_cvt_pk_bf16_f32 v4, v6, v7
	v_cvt_pk_bf16_f32 v5, v8, v9
	global_store_dwordx4 v[18:19], v[2:5], off offset:256
	s_waitcnt lgkmcnt(0)
	s_nop 0
	v_add_f32_e32 v2, v20, v10
	v_mov_b32_e32 v3, v2
	s_nop 1
	v_permlane32_swap_b32_e32 v2, v3
	s_and_saveexec_b64 s[22:23], vcc
	s_cbranch_execz .LBB0_530
	v_add_f32_e32 v2, v2, v3
	v_fma_f32 v2, v2, s74, 0.5
	v_cvt_u32_f32_e32 v2, v2
	global_atomic_add v[146:147], v2, off offset:704

.LBB0_650:
	v_mov_b32_e32 v66, v0
	s_lshl_b32 s0, s22, 8
	s_add_i32 s0, s0, s54
	v_bfe_u32 v240, v66, 4, 2
	v_and_or_b32 v226, v66, 15, s0
	s_or_b32 s0, s6, s67
	v_lshlrev_b32_e32 v66, 3, v240
	v_or_b32_e32 v212, s0, v66
	v_or_b32_e32 v66, s67, v66
	v_ashrrev_i32_e32 v213, 31, v212
	v_ashrrev_i32_e32 v227, 31, v226
	v_lshlrev_b32_e32 v239, 2, v66
	v_lshl_add_u64 v[66:67], v[212:213], 1, s[12:13]
	v_lshlrev_b64 v[68:69], 12, v[226:227]
	v_or_b32_e32 v224, 16, v226
	v_lshl_add_u64 v[68:69], v[66:67], 0, v[68:69]
	v_ashrrev_i32_e32 v225, 31, v224
	global_load_dwordx4 v[228:231], v[68:69], off
	global_load_dwordx4 v[186:189], v[68:69], off offset:256
	v_lshlrev_b64 v[68:69], 12, v[224:225]
	v_or_b32_e32 v222, 32, v226
	v_lshl_add_u64 v[68:69], v[66:67], 0, v[68:69]
	v_ashrrev_i32_e32 v223, 31, v222
	global_load_dwordx4 v[182:185], v[68:69], off
	global_load_dwordx4 v[178:181], v[68:69], off offset:256
	v_lshlrev_b64 v[68:69], 12, v[222:223]
	v_or_b32_e32 v220, 48, v226
	v_lshl_add_u64 v[68:69], v[66:67], 0, v[68:69]
	v_ashrrev_i32_e32 v221, 31, v220
	global_load_dwordx4 v[174:177], v[68:69], off
	global_load_dwordx4 v[170:173], v[68:69], off offset:256
	v_lshlrev_b64 v[68:69], 12, v[220:221]
	v_add_u32_e32 v218, 0x80, v226
	v_lshl_add_u64 v[68:69], v[66:67], 0, v[68:69]
	v_ashrrev_i32_e32 v219, 31, v218
	global_load_dwordx4 v[158:161], v[68:69], off
	global_load_dwordx4 v[154:157], v[68:69], off offset:256
	v_lshlrev_b64 v[68:69], 12, v[218:219]
	v_add_u32_e32 v216, 0x90, v226
	v_lshl_add_u64 v[68:69], v[66:67], 0, v[68:69]
	v_ashrrev_i32_e32 v217, 31, v216
	global_load_dwordx4 v[142:145], v[68:69], off
	global_load_dwordx4 v[130:133], v[68:69], off offset:256
	v_lshlrev_b64 v[68:69], 12, v[216:217]
	v_add_u32_e32 v214, 0xa0, v226
	v_lshl_add_u64 v[68:69], v[66:67], 0, v[68:69]
	v_ashrrev_i32_e32 v215, 31, v214
	global_load_dwordx4 v[118:121], v[68:69], off
	global_load_dwordx4 v[106:109], v[68:69], off offset:256
	v_lshlrev_b64 v[68:69], 12, v[214:215]
	v_add_u32_e32 v210, 0xb0, v226
	v_lshl_add_u64 v[68:69], v[66:67], 0, v[68:69]
	v_ashrrev_i32_e32 v211, 31, v210
	global_load_dwordx4 v[94:97], v[68:69], off
	global_load_dwordx4 v[82:85], v[68:69], off offset:256
	v_lshlrev_b64 v[68:69], 12, v[210:211]
	v_lshl_add_u64 v[66:67], v[66:67], 0, v[68:69]
	global_load_dwordx4 v[70:73], v[66:67], off
	s_nop 0
	global_load_dwordx4 v[66:69], v[66:67], off offset:256
	v_add_u32_e32 v238, 0, v239
	v_add_u32_e32 v238, 0x24400, v238
	v_lshlrev_b64 v[242:243], 11, v[226:227]
	v_lshl_add_u64 v[250:251], v[242:243], 0, v[212:213]
	ds_read_b128 v[242:245], v238
	ds_read_b128 v[246:249], v238 offset:16
	s_andn2_b64 vcc, exec, s[38:39]
	v_add_u32_e32 v239, s59, v239
	s_waitcnt vmcnt(14)
	v_lshlrev_b32_e32 v252, 16, v228
	v_and_b32_e32 v253, 0xffff0000, v228
	v_lshlrev_b32_e32 v228, 16, v229
	v_and_b32_e32 v229, 0xffff0000, v229
	s_waitcnt lgkmcnt(1)
	v_pk_fma_f32 v[168:169], v[168:169], v[244:245], v[228:229]
	v_lshlrev_b32_e32 v228, 16, v230
	v_and_b32_e32 v229, 0xffff0000, v230
	v_lshlrev_b32_e32 v230, 16, v231
	v_and_b32_e32 v231, 0xffff0000, v231
	v_pk_fma_f32 v[166:167], v[166:167], v[242:243], v[252:253]
	s_waitcnt lgkmcnt(0)
	v_pk_fma_f32 v[164:165], v[164:165], v[248:249], v[230:231]
	v_pk_fma_f32 v[162:163], v[162:163], v[246:247], v[228:229]
	v_cndmask_b32_e64 v230, 0, 1, s[38:39]
	v_cvt_pk_bf16_f32 v242, v166, v167
	v_cvt_pk_bf16_f32 v243, v168, v169
	v_cvt_pk_bf16_f32 v244, v162, v163
	v_cvt_pk_bf16_f32 v245, v164, v165
	v_lshl_add_u64 v[162:163], v[250:251], 1, s[36:37]
	v_lshlrev_b32_e32 v228, 16, v242
	v_and_b32_e32 v229, 0xffff0000, v242
	v_lshlrev_b32_e32 v168, 16, v243
	v_and_b32_e32 v169, 0xffff0000, v243
	v_lshlrev_b32_e32 v166, 16, v244
	v_and_b32_e32 v167, 0xffff0000, v244
	v_lshlrev_b32_e32 v164, 16, v245
	v_and_b32_e32 v165, 0xffff0000, v245
	v_cmp_ne_u32_e64 s[6:7], 1, v230
	v_lshl_add_u64 v[230:231], v[250:251], 1, s[46:47]
	global_store_dwordx4 v[162:163], v[242:245], off
	s_cbranch_vccnz .LBB0_652
	ds_read_b128 v[242:245], v239 offset:1024
	ds_read_b128 v[246:249], v239 offset:1040
	s_waitcnt lgkmcnt(1)
	v_pk_mul_f32 v[244:245], v[168:169], v[244:245]
	v_pk_mul_f32 v[242:243], v[228:229], v[242:243]
	s_waitcnt lgkmcnt(0)
	v_pk_mul_f32 v[248:249], v[164:165], v[248:249]
	v_pk_mul_f32 v[246:247], v[166:167], v[246:247]
	v_cvt_pk_bf16_f32 v242, v242, v243
	v_cvt_pk_bf16_f32 v243, v244, v245
	s_nop 0
	v_cvt_pk_bf16_f32 v244, v246, v247
	v_cvt_pk_bf16_f32 v245, v248, v249
	global_store_dwordx4 v[230:231], v[242:245], off

.LBB0_656:
	s_or_b64 exec, exec, s[22:23]
	v_lshlrev_b64 v[146:147], 11, v[224:225]
	v_lshl_add_u64 v[162:163], v[146:147], 0, v[212:213]
	ds_read_b128 v[146:149], v238
	ds_read_b128 v[150:153], v238 offset:16
	s_waitcnt vmcnt(15)
	v_lshlrev_b32_e32 v164, 16, v182
	v_and_b32_e32 v165, 0xffff0000, v182
	v_lshlrev_b32_e32 v166, 16, v183
	v_and_b32_e32 v167, 0xffff0000, v183
	s_waitcnt lgkmcnt(1)
	v_pk_fma_f32 v[140:141], v[140:141], v[148:149], v[166:167]
	v_pk_fma_f32 v[138:139], v[138:139], v[146:147], v[164:165]
	v_lshlrev_b32_e32 v146, 16, v184
	v_and_b32_e32 v147, 0xffff0000, v184
	v_lshlrev_b32_e32 v148, 16, v185
	v_and_b32_e32 v149, 0xffff0000, v185
	s_waitcnt lgkmcnt(0)
	v_pk_fma_f32 v[136:137], v[136:137], v[152:153], v[148:149]
	v_pk_fma_f32 v[134:135], v[134:135], v[150:151], v[146:147]
	v_cvt_pk_bf16_f32 v150, v138, v139
	v_cvt_pk_bf16_f32 v151, v140, v141
	v_lshl_add_u64 v[148:149], v[162:163], 1, s[36:37]
	v_cvt_pk_bf16_f32 v152, v134, v135
	v_cvt_pk_bf16_f32 v153, v136, v137
	v_lshlrev_b32_e32 v140, 16, v150
	v_and_b32_e32 v141, 0xffff0000, v150
	v_lshlrev_b32_e32 v138, 16, v151
	v_and_b32_e32 v139, 0xffff0000, v151
	v_lshlrev_b32_e32 v136, 16, v152
	v_and_b32_e32 v137, 0xffff0000, v152
	v_lshlrev_b32_e32 v134, 16, v153
	v_and_b32_e32 v135, 0xffff0000, v153
	s_and_b64 vcc, exec, s[6:7]
	v_lshl_add_u64 v[146:147], v[162:163], 1, s[46:47]
	global_store_dwordx4 v[148:149], v[150:153], off
	s_cbranch_vccnz .LBB0_658
	ds_read_b128 v[150:153], v239 offset:1024
	ds_read_b128 v[162:165], v239 offset:1040
	s_waitcnt lgkmcnt(1)
	v_pk_mul_f32 v[152:153], v[138:139], v[152:153]
	v_pk_mul_f32 v[150:151], v[140:141], v[150:151]
	s_waitcnt lgkmcnt(0)
	v_pk_mul_f32 v[164:165], v[134:135], v[164:165]
	v_pk_mul_f32 v[162:163], v[136:137], v[162:163]
	v_cvt_pk_bf16_f32 v150, v150, v151
	v_cvt_pk_bf16_f32 v151, v152, v153
	s_nop 0
	v_cvt_pk_bf16_f32 v152, v162, v163
	v_cvt_pk_bf16_f32 v153, v164, v165
	global_store_dwordx4 v[146:147], v[150:153], off

.LBB0_662:
	s_or_b64 exec, exec, s[22:23]
	v_lshlrev_b64 v[122:123], 11, v[222:223]
	v_lshl_add_u64 v[134:135], v[122:123], 0, v[212:213]
	ds_read_b128 v[122:125], v238
	ds_read_b128 v[126:129], v238 offset:16
	s_waitcnt vmcnt(16)
	v_lshlrev_b32_e32 v136, 16, v174
	v_and_b32_e32 v137, 0xffff0000, v174
	v_lshlrev_b32_e32 v138, 16, v175
	v_and_b32_e32 v139, 0xffff0000, v175
	s_waitcnt lgkmcnt(1)
	v_pk_fma_f32 v[116:117], v[116:117], v[124:125], v[138:139]
	v_pk_fma_f32 v[114:115], v[114:115], v[122:123], v[136:137]
	v_lshlrev_b32_e32 v122, 16, v176
	v_and_b32_e32 v123, 0xffff0000, v176
	v_lshlrev_b32_e32 v124, 16, v177
	v_and_b32_e32 v125, 0xffff0000, v177
	s_waitcnt lgkmcnt(0)
	v_pk_fma_f32 v[112:113], v[112:113], v[128:129], v[124:125]
	v_pk_fma_f32 v[110:111], v[110:111], v[126:127], v[122:123]
	v_cvt_pk_bf16_f32 v126, v114, v115
	v_cvt_pk_bf16_f32 v127, v116, v117
	v_lshl_add_u64 v[124:125], v[134:135], 1, s[36:37]
	v_cvt_pk_bf16_f32 v128, v110, v111
	v_cvt_pk_bf16_f32 v129, v112, v113
	v_lshlrev_b32_e32 v116, 16, v126
	v_and_b32_e32 v117, 0xffff0000, v126
	v_lshlrev_b32_e32 v114, 16, v127
	v_and_b32_e32 v115, 0xffff0000, v127
	v_lshlrev_b32_e32 v112, 16, v128
	v_and_b32_e32 v113, 0xffff0000, v128
	v_lshlrev_b32_e32 v110, 16, v129
	v_and_b32_e32 v111, 0xffff0000, v129
	s_and_b64 vcc, exec, s[6:7]
	v_lshl_add_u64 v[122:123], v[134:135], 1, s[46:47]
	global_store_dwordx4 v[124:125], v[126:129], off
	s_cbranch_vccnz .LBB0_664
	ds_read_b128 v[126:129], v239 offset:1024
	ds_read_b128 v[134:137], v239 offset:1040
	s_waitcnt lgkmcnt(1)
	v_pk_mul_f32 v[128:129], v[114:115], v[128:129]
	v_pk_mul_f32 v[126:127], v[116:117], v[126:127]
	s_waitcnt lgkmcnt(0)
	v_pk_mul_f32 v[136:137], v[110:111], v[136:137]
	v_pk_mul_f32 v[134:135], v[112:113], v[134:135]
	v_cvt_pk_bf16_f32 v126, v126, v127
	v_cvt_pk_bf16_f32 v127, v128, v129
	s_nop 0
	v_cvt_pk_bf16_f32 v128, v134, v135
	v_cvt_pk_bf16_f32 v129, v136, v137
	global_store_dwordx4 v[122:123], v[126:129], off

.LBB0_668:
	s_or_b64 exec, exec, s[22:23]
	v_lshlrev_b64 v[98:99], 11, v[220:221]
	v_lshl_add_u64 v[110:111], v[98:99], 0, v[212:213]
	ds_read_b128 v[98:101], v238
	ds_read_b128 v[102:105], v238 offset:16
	s_waitcnt vmcnt(17)
	v_lshlrev_b32_e32 v112, 16, v158
	v_and_b32_e32 v113, 0xffff0000, v158
	v_lshlrev_b32_e32 v114, 16, v159
	v_and_b32_e32 v115, 0xffff0000, v159
	s_waitcnt lgkmcnt(1)
	v_pk_fma_f32 v[92:93], v[92:93], v[100:101], v[114:115]
	v_pk_fma_f32 v[90:91], v[90:91], v[98:99], v[112:113]
	v_lshlrev_b32_e32 v98, 16, v160
	v_and_b32_e32 v99, 0xffff0000, v160
	v_lshlrev_b32_e32 v100, 16, v161
	v_and_b32_e32 v101, 0xffff0000, v161
	s_waitcnt lgkmcnt(0)
	v_pk_fma_f32 v[88:89], v[88:89], v[104:105], v[100:101]
	v_pk_fma_f32 v[86:87], v[86:87], v[102:103], v[98:99]
	v_cvt_pk_bf16_f32 v102, v90, v91
	v_cvt_pk_bf16_f32 v103, v92, v93
	v_lshl_add_u64 v[100:101], v[110:111], 1, s[36:37]
	v_cvt_pk_bf16_f32 v104, v86, v87
	v_cvt_pk_bf16_f32 v105, v88, v89
	v_lshlrev_b32_e32 v92, 16, v102
	v_and_b32_e32 v93, 0xffff0000, v102
	v_lshlrev_b32_e32 v90, 16, v103
	v_and_b32_e32 v91, 0xffff0000, v103
	v_lshlrev_b32_e32 v88, 16, v104
	v_and_b32_e32 v89, 0xffff0000, v104
	v_lshlrev_b32_e32 v86, 16, v105
	v_and_b32_e32 v87, 0xffff0000, v105
	s_and_b64 vcc, exec, s[6:7]
	v_lshl_add_u64 v[98:99], v[110:111], 1, s[46:47]
	global_store_dwordx4 v[100:101], v[102:105], off
	s_cbranch_vccnz .LBB0_670
	ds_read_b128 v[102:105], v239 offset:1024
	ds_read_b128 v[110:113], v239 offset:1040
	s_waitcnt lgkmcnt(1)
	v_pk_mul_f32 v[104:105], v[90:91], v[104:105]
	v_pk_mul_f32 v[102:103], v[92:93], v[102:103]
	s_waitcnt lgkmcnt(0)
	v_pk_mul_f32 v[112:113], v[86:87], v[112:113]
	v_pk_mul_f32 v[110:111], v[88:89], v[110:111]
	v_cvt_pk_bf16_f32 v102, v102, v103
	v_cvt_pk_bf16_f32 v103, v104, v105
	s_nop 0
	v_cvt_pk_bf16_f32 v104, v110, v111
	v_cvt_pk_bf16_f32 v105, v112, v113
	global_store_dwordx4 v[98:99], v[102:105], off

.LBB0_674:
	s_or_b64 exec, exec, s[22:23]
	v_lshlrev_b64 v[74:75], 11, v[218:219]
	v_lshl_add_u64 v[86:87], v[74:75], 0, v[212:213]
	ds_read_b128 v[74:77], v238
	ds_read_b128 v[78:81], v238 offset:16
	s_waitcnt vmcnt(18)
	v_lshlrev_b32_e32 v88, 16, v142
	v_and_b32_e32 v89, 0xffff0000, v142
	v_lshlrev_b32_e32 v90, 16, v143
	v_and_b32_e32 v91, 0xffff0000, v143
	s_waitcnt lgkmcnt(1)
	v_pk_fma_f32 v[64:65], v[64:65], v[76:77], v[90:91]
	v_pk_fma_f32 v[62:63], v[62:63], v[74:75], v[88:89]
	v_lshlrev_b32_e32 v74, 16, v144
	v_and_b32_e32 v75, 0xffff0000, v144
	v_lshlrev_b32_e32 v76, 16, v145
	v_and_b32_e32 v77, 0xffff0000, v145
	s_waitcnt lgkmcnt(0)
	v_pk_fma_f32 v[60:61], v[60:61], v[80:81], v[76:77]
	v_pk_fma_f32 v[58:59], v[58:59], v[78:79], v[74:75]
	v_cvt_pk_bf16_f32 v78, v62, v63
	v_cvt_pk_bf16_f32 v79, v64, v65
	v_lshl_add_u64 v[76:77], v[86:87], 1, s[36:37]
	v_cvt_pk_bf16_f32 v80, v58, v59
	v_cvt_pk_bf16_f32 v81, v60, v61
	v_lshlrev_b32_e32 v64, 16, v78
	v_and_b32_e32 v65, 0xffff0000, v78
	v_lshlrev_b32_e32 v62, 16, v79
	v_and_b32_e32 v63, 0xffff0000, v79
	v_lshlrev_b32_e32 v60, 16, v80
	v_and_b32_e32 v61, 0xffff0000, v80
	v_lshlrev_b32_e32 v58, 16, v81
	v_and_b32_e32 v59, 0xffff0000, v81
	s_and_b64 vcc, exec, s[6:7]
	v_lshl_add_u64 v[74:75], v[86:87], 1, s[46:47]
	global_store_dwordx4 v[76:77], v[78:81], off
	s_cbranch_vccnz .LBB0_676
	ds_read_b128 v[78:81], v239 offset:1024
	ds_read_b128 v[86:89], v239 offset:1040
	s_waitcnt lgkmcnt(1)
	v_pk_mul_f32 v[80:81], v[62:63], v[80:81]
	v_pk_mul_f32 v[78:79], v[64:65], v[78:79]
	s_waitcnt lgkmcnt(0)
	v_pk_mul_f32 v[88:89], v[58:59], v[88:89]
	v_pk_mul_f32 v[86:87], v[60:61], v[86:87]
	v_cvt_pk_bf16_f32 v78, v78, v79
	v_cvt_pk_bf16_f32 v79, v80, v81
	s_nop 0
	v_cvt_pk_bf16_f32 v80, v86, v87
	v_cvt_pk_bf16_f32 v81, v88, v89
	global_store_dwordx4 v[74:75], v[78:81], off

.LBB0_680:
	s_or_b64 exec, exec, s[22:23]
	v_lshlrev_b64 v[50:51], 11, v[216:217]
	v_lshl_add_u64 v[58:59], v[50:51], 0, v[212:213]
	ds_read_b128 v[50:53], v238
	ds_read_b128 v[54:57], v238 offset:16
	s_waitcnt vmcnt(19)
	v_lshlrev_b32_e32 v60, 16, v118
	v_and_b32_e32 v61, 0xffff0000, v118
	v_lshlrev_b32_e32 v62, 16, v119
	v_and_b32_e32 v63, 0xffff0000, v119
	s_waitcnt lgkmcnt(1)
	v_pk_fma_f32 v[48:49], v[48:49], v[52:53], v[62:63]
	v_pk_fma_f32 v[46:47], v[46:47], v[50:51], v[60:61]
	v_lshlrev_b32_e32 v50, 16, v120
	v_and_b32_e32 v51, 0xffff0000, v120
	v_lshlrev_b32_e32 v52, 16, v121
	v_and_b32_e32 v53, 0xffff0000, v121
	s_waitcnt lgkmcnt(0)
	v_pk_fma_f32 v[44:45], v[44:45], v[56:57], v[52:53]
	v_pk_fma_f32 v[42:43], v[42:43], v[54:55], v[50:51]
	v_cvt_pk_bf16_f32 v54, v46, v47
	v_cvt_pk_bf16_f32 v55, v48, v49
	v_lshl_add_u64 v[52:53], v[58:59], 1, s[36:37]
	v_cvt_pk_bf16_f32 v56, v42, v43
	v_cvt_pk_bf16_f32 v57, v44, v45
	v_lshlrev_b32_e32 v48, 16, v54
	v_and_b32_e32 v49, 0xffff0000, v54
	v_lshlrev_b32_e32 v46, 16, v55
	v_and_b32_e32 v47, 0xffff0000, v55
	v_lshlrev_b32_e32 v44, 16, v56
	v_and_b32_e32 v45, 0xffff0000, v56
	v_lshlrev_b32_e32 v42, 16, v57
	v_and_b32_e32 v43, 0xffff0000, v57
	s_and_b64 vcc, exec, s[6:7]
	v_lshl_add_u64 v[50:51], v[58:59], 1, s[46:47]
	global_store_dwordx4 v[52:53], v[54:57], off
	s_cbranch_vccnz .LBB0_682
	ds_read_b128 v[54:57], v239 offset:1024
	ds_read_b128 v[58:61], v239 offset:1040
	s_waitcnt lgkmcnt(1)
	v_pk_mul_f32 v[56:57], v[46:47], v[56:57]
	v_pk_mul_f32 v[54:55], v[48:49], v[54:55]
	s_waitcnt lgkmcnt(0)
	v_pk_mul_f32 v[60:61], v[42:43], v[60:61]
	v_pk_mul_f32 v[58:59], v[44:45], v[58:59]
	v_cvt_pk_bf16_f32 v54, v54, v55
	v_cvt_pk_bf16_f32 v55, v56, v57
	s_nop 0
	v_cvt_pk_bf16_f32 v56, v58, v59
	v_cvt_pk_bf16_f32 v57, v60, v61
	global_store_dwordx4 v[50:51], v[54:57], off

.LBB0_686:
	s_or_b64 exec, exec, s[22:23]
	v_lshlrev_b64 v[34:35], 11, v[214:215]
	v_lshl_add_u64 v[42:43], v[34:35], 0, v[212:213]
	ds_read_b128 v[34:37], v238
	ds_read_b128 v[38:41], v238 offset:16
	s_waitcnt vmcnt(20)
	v_lshlrev_b32_e32 v44, 16, v94
	v_and_b32_e32 v45, 0xffff0000, v94
	v_lshlrev_b32_e32 v46, 16, v95
	v_and_b32_e32 v47, 0xffff0000, v95
	s_waitcnt lgkmcnt(1)
	v_pk_fma_f32 v[32:33], v[32:33], v[36:37], v[46:47]
	v_pk_fma_f32 v[30:31], v[30:31], v[34:35], v[44:45]
	v_lshlrev_b32_e32 v34, 16, v96
	v_and_b32_e32 v35, 0xffff0000, v96
	v_lshlrev_b32_e32 v36, 16, v97
	v_and_b32_e32 v37, 0xffff0000, v97
	s_waitcnt lgkmcnt(0)
	v_pk_fma_f32 v[28:29], v[28:29], v[40:41], v[36:37]
	v_pk_fma_f32 v[26:27], v[26:27], v[38:39], v[34:35]
	v_cvt_pk_bf16_f32 v38, v30, v31
	v_cvt_pk_bf16_f32 v39, v32, v33
	v_lshl_add_u64 v[36:37], v[42:43], 1, s[36:37]
	v_cvt_pk_bf16_f32 v40, v26, v27
	v_cvt_pk_bf16_f32 v41, v28, v29
	v_lshlrev_b32_e32 v32, 16, v38
	v_and_b32_e32 v33, 0xffff0000, v38
	v_lshlrev_b32_e32 v30, 16, v39
	v_and_b32_e32 v31, 0xffff0000, v39
	v_lshlrev_b32_e32 v28, 16, v40
	v_and_b32_e32 v29, 0xffff0000, v40
	v_lshlrev_b32_e32 v26, 16, v41
	v_and_b32_e32 v27, 0xffff0000, v41
	s_and_b64 vcc, exec, s[6:7]
	v_lshl_add_u64 v[34:35], v[42:43], 1, s[46:47]
	global_store_dwordx4 v[36:37], v[38:41], off
	s_cbranch_vccnz .LBB0_688
	ds_read_b128 v[38:41], v239 offset:1024
	ds_read_b128 v[42:45], v239 offset:1040
	s_waitcnt lgkmcnt(1)
	v_pk_mul_f32 v[40:41], v[30:31], v[40:41]
	v_pk_mul_f32 v[38:39], v[32:33], v[38:39]
	s_waitcnt lgkmcnt(0)
	v_pk_mul_f32 v[44:45], v[26:27], v[44:45]
	v_pk_mul_f32 v[42:43], v[28:29], v[42:43]
	v_cvt_pk_bf16_f32 v38, v38, v39
	v_cvt_pk_bf16_f32 v39, v40, v41
	s_nop 0
	v_cvt_pk_bf16_f32 v40, v42, v43
	v_cvt_pk_bf16_f32 v41, v44, v45
	global_store_dwordx4 v[34:35], v[38:41], off

.LBB0_692:
	s_or_b64 exec, exec, s[22:23]
	v_lshlrev_b64 v[18:19], 11, v[210:211]
	v_lshl_add_u64 v[26:27], v[18:19], 0, v[212:213]
	ds_read_b128 v[18:21], v238
	ds_read_b128 v[22:25], v238 offset:16
	s_waitcnt vmcnt(21)
	v_lshlrev_b32_e32 v28, 16, v70
	v_and_b32_e32 v29, 0xffff0000, v70
	v_lshlrev_b32_e32 v30, 16, v71
	v_and_b32_e32 v31, 0xffff0000, v71
	s_waitcnt lgkmcnt(1)
	v_pk_fma_f32 v[16:17], v[16:17], v[20:21], v[30:31]
	v_pk_fma_f32 v[14:15], v[14:15], v[18:19], v[28:29]
	v_lshlrev_b32_e32 v18, 16, v72
	v_and_b32_e32 v19, 0xffff0000, v72
	v_lshlrev_b32_e32 v20, 16, v73
	v_and_b32_e32 v21, 0xffff0000, v73
	s_waitcnt lgkmcnt(0)
	v_pk_fma_f32 v[12:13], v[12:13], v[24:25], v[20:21]
	v_pk_fma_f32 v[10:11], v[10:11], v[22:23], v[18:19]
	v_cvt_pk_bf16_f32 v22, v14, v15
	v_cvt_pk_bf16_f32 v23, v16, v17
	v_lshl_add_u64 v[20:21], v[26:27], 1, s[36:37]
	v_cvt_pk_bf16_f32 v24, v10, v11
	v_cvt_pk_bf16_f32 v25, v12, v13
	v_lshlrev_b32_e32 v16, 16, v22
	v_and_b32_e32 v17, 0xffff0000, v22
	v_lshlrev_b32_e32 v14, 16, v23
	v_and_b32_e32 v15, 0xffff0000, v23
	v_lshlrev_b32_e32 v12, 16, v24
	v_and_b32_e32 v13, 0xffff0000, v24
	v_lshlrev_b32_e32 v10, 16, v25
	v_and_b32_e32 v11, 0xffff0000, v25
	s_and_b64 vcc, exec, s[6:7]
	v_lshl_add_u64 v[18:19], v[26:27], 1, s[46:47]
	global_store_dwordx4 v[20:21], v[22:25], off
	s_cbranch_vccnz .LBB0_694
	ds_read_b128 v[22:25], v239 offset:1024
	ds_read_b128 v[26:29], v239 offset:1040
	s_waitcnt lgkmcnt(1)
	v_pk_mul_f32 v[24:25], v[14:15], v[24:25]
	v_pk_mul_f32 v[22:23], v[16:17], v[22:23]
	s_waitcnt lgkmcnt(0)
	v_pk_mul_f32 v[28:29], v[10:11], v[28:29]
	v_pk_mul_f32 v[26:27], v[12:13], v[26:27]
	v_cvt_pk_bf16_f32 v22, v22, v23
	v_cvt_pk_bf16_f32 v23, v24, v25
	s_nop 0
	v_cvt_pk_bf16_f32 v24, v26, v27
	v_cvt_pk_bf16_f32 v25, v28, v29
	global_store_dwordx4 v[18:19], v[22:25], off
